# conversion split: only w_in[0] converted in the prologue; layer-0 w_out/gate-up/down weights converted by the idle CUs of scan 0 (they are first used after it)
# speedup vs baseline: 1.0209x; 1.0209x over previous
; #define LAS __attribute__((address_space(3)))
; DI void phase_prologue(const Frame& F0, const Args& a) {
;     ...
;         LAS float* scr = (LAS float*)(F.lds + 43008 + F.wave * 8448);
;         const int gw = F.vcu * NWAVES + F.wave, NGW = F.G * NWAVES;
;         constexpr int I_IN = 32 * (GIN / 32), I_SQ = 32 * 64, I_GU = 32 * (2 * DFF / 32), I_DN = (DFF / 64) * 64;
;         constexpr int NITEMS = 2 * I_IN + 2 * I_SQ + 2 * I_SQ + DEPTH * I_GU + DEPTH * I_DN;
;         for (int it = gw; it < NITEMS; it += NGW) {
;             int r = it;
.LBB0_79:
	s_or_b64 exec, exec, s[8:9]
	s_lshl_b32 s0, s60, 3
	s_add_i32 s6, s0, s44
	s_cmp_gt_i32 s6, 0x1583f
	s_cbranch_scc1 .LBB0_11
	s_mov_b32 s90, s6
	s_mov_b32 s92, 0
	s_mov_b32 s91, 0x15840
	v_readlane_b32 s93, v252, 53
	s_cmp_eq_u32 s3, 0x100
	s_cbranch_scc0 .Lconv_entry
	s_mov_b32 s92, 1
	s_mov_b32 s91, 0x1820

; DI void phase_prologue(const Frame& F0, const Args& a) {
;     ...
;         for (int it = gw; it < NITEMS; it += NGW) {
;             int r = it;
;             if (r < 2 * I_IN) { const int j = r / I_IN; r %= I_IN; const int nblk = GIN / 32, kb = r / nblk, nb = r % nblk;
;                 transpose_item(a.gla_w_in + (size_t)j * DM * GIN, DM, GIN, (bf16*)(ws + WS_WIN) + (size_t)j * GIN_PAD * DM, 64 * kb, 32 * nb, 32 * nb, scr, F.lane); continue; }
;             r -= 2 * I_IN;
;             if (r < 2 * I_SQ) { const int j = r / I_SQ; r %= I_SQ; const int kb = r / 64, nb = r % 64;
;                 transpose_item(a.gla_w_out + (size_t)j * DM * DM, DM, DM, (bf16*)(ws + WS_WGO) + (size_t)j * DM * DM, 64 * kb, 32 * nb, 32 * nb, scr, F.lane); continue; }
;             r -= 2 * I_SQ;
;             if (r < 2 * I_SQ) { const int j = r / I_SQ; r %= I_SQ; const int kb = r / 64, nb = r % 64;
;                 transpose_item(a.fnet_w_out + (size_t)j * DM * DM, DM, DM, (bf16*)(ws + WS_WFO) + (size_t)j * DM * DM, 64 * kb, 32 * nb, 32 * nb, scr, F.lane, 1); continue; }
;             r -= 2 * I_SQ;
;             if (r < DEPTH * I_GU) { const int j = r / I_GU; r %= I_GU; const int nblk = 2 * DFF / 32, kb = r / nblk, nb = r % nblk, n0 = 32 * nb;
;                 const int jj = n0 < DFF ? n0 : n0 - DFF; const int drow = (jj >> 7) * 256 + (n0 < DFF ? 0 : 128) + (jj & 127);
;                 transpose_item(a.ffn_w_gu + (size_t)j * DM * 2 * DFF, DM, 2 * DFF, (bf16*)(ws + WS_WGU) + (size_t)j * 2 * DFF * DM, 64 * kb, n0, drow, scr, F.lane); continue; }
;             r -= DEPTH * I_GU;
;             { const int j = r / I_DN; r %= I_DN; const int kb = r / 64, nb = r % 64;
;                 transpose_item(a.ffn_w_down + (size_t)j * DFF * DM, DFF, DM, (bf16*)(ws + WS_WDN) + (size_t)j * DM * DFF, 64 * kb, 32 * nb, 32 * nb, scr, F.lane); }
.Lcv_map1:
	s_mov_b32 s0, 0x0
	s_add_i32 s6, s94, s0
	s_branch .Lcv_mapped
.Lcv_map2:
	s_mov_b32 s0, 0x8020
	s_cmp_lt_i32 s94, 0x8020
	s_cselect_b32 s0, 0x2820, s0
	s_cmp_lt_i32 s94, 0x2820
	s_cselect_b32 s0, 0x2020, s0
	s_cmp_lt_i32 s94, 0x2020
	s_cselect_b32 s0, 0x1820, s0
	s_add_i32 s6, s94, s0
	s_branch .Lcv_mapped
.Lcv_map3:
	s_mov_b32 s0, 0xc440
	s_cmp_lt_i32 s94, 0x6800
	s_cselect_b32 s0, 0x9840, s0
	s_cmp_lt_i32 s94, 0x1000
	s_cselect_b32 s0, 0x4040, s0
	s_cmp_lt_i32 s94, 0x800
	s_cselect_b32 s0, 0x3840, s0
	s_add_i32 s6, s94, s0
	s_branch .Lcv_mapped

; DI void phase_prologue(const Frame& F0, const Args& a) {
;     ...
;         const int gw = F.vcu * NWAVES + F.wave, NGW = F.G * NWAVES;
;         constexpr int I_IN = 32 * (GIN / 32), I_SQ = 32 * 64, I_GU = 32 * (2 * DFF / 32), I_DN = (DFF / 64) * 64;
;         constexpr int NITEMS = 2 * I_IN + 2 * I_SQ + 2 * I_SQ + DEPTH * I_GU + DEPTH * I_DN;
;         for (int it = gw; it < NITEMS; it += NGW) {
; DI void phase_scan(const Frame& F0, const Args& a, int colmajor) {
;     ...
;     for (int it = F.vcu; it < 256; it += F.G) {
;         if ((it & 31) >= 16) continue;
.Lconv_scan_idle:
	s_cmp_eq_u32 s3, 0x100
	s_cbranch_scc0 .LBB0_821
	v_writelane_b32 v100, s11, 0
	v_writelane_b32 v100, s20, 1
	v_writelane_b32 v100, s21, 2
	v_writelane_b32 v100, s22, 3
	v_writelane_b32 v100, s26, 4
	v_writelane_b32 v100, s28, 5
	v_writelane_b32 v100, s29, 6
	v_writelane_b32 v100, s30, 7
	v_writelane_b32 v100, s44, 8
	v_writelane_b32 v100, s86, 9
	v_writelane_b32 v100, s87, 10
	v_mov_b32_e32 v101, v1
	v_mov_b32_e32 v102, v3
	v_readlane_b32 s0, v255, 17
	v_readlane_b32 s1, v252, 48
	v_readlane_b32 s44, v252, 49
	v_readlane_b32 s86, v252, 46
	v_readlane_b32 s87, v252, 47
	v_mov_b32_e32 v78, v222
	s_lshr_b32 s4, s1, 5
	s_lshl_b32 s4, s4, 4
	s_and_b32 s5, s1, 15
	s_or_b32 s4, s4, s5
	s_cmp_ge_u32 s44, 8
	s_cbranch_scc1 .Lconv_ret_scan
	s_mul_i32 s4, s4, 8
	s_add_i32 s90, s4, s44
	s_movk_i32 s93, 0x400
	s_mov_b32 s4, 0xac20
	s_mov_b32 s5, 0x9400
	s_cmp_eq_u32 s0, 0
	s_cselect_b32 s92, 2, 3
	s_cselect_b32 s91, s4, s5
	s_cmp_lt_i32 s90, s91
	s_cbranch_scc1 .Lconv_entry
